# GEMM SP2/SP1b load segments: remaining pointer arithmetic moved behind the ds_reads and into the M0 wait-state slots
# baseline (speedup 1.0000x reference)
; #define PG8_STAGE(bufoff, gbase, voff) do { _Pragma("unroll") for (int _i = 0; _i < 2; ++_i) \
;         __builtin_amdgcn_global_load_lds((const unsigned*)((const char*)(gbase) + (voff)[_i]), (PG8_LAS unsigned*)(lds + (bufoff) + ldsw + _i * 8192), 16, 0, 0); } while (0)
; #define PG8_LDA(dst, b, h) do { _Pragma("unroll") for (int m = 0; m < 4; ++m) _Pragma("unroll") for (int k = 0; k < 2; ++k) dst[m][k] = *(const PG8_LAS bf16x8*)(lds + PG8_SA(b, h) + aoff + m * 2048 + k * 1024); } while (0)
; #define PG8_MMA(ai, bj, At, Bt) do { __builtin_amdgcn_s_setprio(1); _Pragma("unroll") for (int m = 0; m < 4; ++m) _Pragma("unroll") for (int n = 0; n < 2; ++n) _Pragma("unroll") for (int k = 0; k < 2; ++k) \
;         acc[ai][bj][m][n] = __builtin_amdgcn_mfma_f32_16x16x32_bf16(Bt[n][k], At[m][k], acc[ai][bj][m][n], 0, 0, 0); __builtin_amdgcn_s_setprio(0); } while (0)
; #define PG8_WAIT_V(n) asm volatile("s_waitcnt vmcnt(" #n ")" ::: "memory")
; #define PG8_WAIT_L(n) asm volatile("s_waitcnt lgkmcnt(" #n ")" ::: "memory")
; #define PG8_BAR __builtin_amdgcn_s_barrier()
; #define PG8_SCHED __builtin_amdgcn_sched_barrier(0)
; template <class Epi, class Sched, bool ALIGN_EPI = false, bool SP2 = false>
; __device__ __forceinline__ void gemm_phase(PG8_LAS unsigned char* lds, const Gemm g, const Sched& S, const Epi& E, const int tid_in) {
;     ...
;             PG8_WAIT_V(8); PG8_WAIT_L(0); PG8_BAR; PG8_MMA(0, 0, At, B0); PG8_MMA(0, 1, At, B1); PG8_BAR; PG8_SCHED;
;             PG8_LDA(At, 0, 1); PG8_STAGE(PG8_SB(0, 0), b2, voffB); PG8_STAGE(PG8_SB(0, 1), b2 + hstep, voffB); PG8_STAGE(PG8_SA(0, 0), a2, voffA);
;             PG8_WAIT_V(8); PG8_WAIT_L(0); PG8_BAR; PG8_MMA(1, 0, At, B0); PG8_MMA(1, 1, At, B1); PG8_BAR; PG8_SCHED;
.LBB0_115:
	ds_read_b128 v[134:137], v248
	ds_read_b128 v[138:141], v248 offset:1024
	ds_read_b128 v[142:145], v248 offset:2048
	ds_read_b128 v[146:149], v248 offset:3072
	ds_read_b128 v[150:153], v249
	ds_read_b128 v[154:157], v249 offset:1024
	ds_read_b128 v[158:161], v249 offset:2048
	ds_read_b128 v[180:183], v249 offset:3072
	ds_read_b128 v[184:187], v179
	ds_read_b128 v[188:191], v179 offset:1024
	ds_read_b128 v[192:195], v179 offset:2048
	ds_read_b128 v[196:199], v179 offset:3072
	ds_read_b128 v[200:203], v179 offset:4096
	ds_read_b128 v[204:207], v179 offset:5120
	ds_read_b128 v[208:211], v179 offset:6144
	ds_read_b128 v[212:215], v179 offset:7168
	s_add_i32 m0, s60, 0xc000
	s_add_i32 s77, s52, 2
	s_add_u32 vcc_lo, s2, s10
	s_addc_u32 s53, s3, s11
	s_add_u32 s44, s50, s10
	s_addc_u32 s45, s51, s11
	s_cmp_eq_u32 s68, s52
	s_cselect_b32 s53, s49, s53
	s_cselect_b32 s52, s48, vcc_lo
	s_cselect_b32 vcc_hi, s43, s45
	s_cselect_b32 vcc_lo, s42, s44
	s_add_i32 s16, 0, 0x10000
	s_add_i32 s17, 0, 0x14000
	global_load_lds_dwordx4 v132, s[2:3]
	s_add_i32 m0, s60, 0xe000
	s_nop 0
	global_load_lds_dwordx4 v130, s[2:3]
	s_waitcnt vmcnt(8)
	s_waitcnt lgkmcnt(0)
	s_barrier
	s_setprio 1
	s_waitcnt lgkmcnt(0)
	v_mfma_f32_16x16x32_bf16 v[126:129], v[134:137], v[184:187], v[126:129]
	v_mfma_f32_16x16x32_bf16 v[122:125], v[142:145], v[184:187], v[122:125]
	v_mfma_f32_16x16x32_bf16 v[110:113], v[134:137], v[192:195], v[110:113]
	v_mfma_f32_16x16x32_bf16 v[106:109], v[142:145], v[192:195], v[106:109]
	v_mfma_f32_16x16x32_bf16 v[94:97], v[134:137], v[200:203], v[94:97]
	v_mfma_f32_16x16x32_bf16 v[90:93], v[142:145], v[200:203], v[90:93]
	v_mfma_f32_16x16x32_bf16 v[78:81], v[134:137], v[208:211], v[78:81]
	v_mfma_f32_16x16x32_bf16 v[74:77], v[142:145], v[208:211], v[74:77]
	v_mfma_f32_16x16x32_bf16 v[126:129], v[138:141], v[188:191], v[126:129]
	v_mfma_f32_16x16x32_bf16 v[122:125], v[146:149], v[188:191], v[122:125]
	v_mfma_f32_16x16x32_bf16 v[110:113], v[138:141], v[196:199], v[110:113]
	v_mfma_f32_16x16x32_bf16 v[106:109], v[146:149], v[196:199], v[106:109]
	v_mfma_f32_16x16x32_bf16 v[94:97], v[138:141], v[204:207], v[94:97]
	v_mfma_f32_16x16x32_bf16 v[90:93], v[146:149], v[204:207], v[90:93]
	v_mfma_f32_16x16x32_bf16 v[78:81], v[138:141], v[212:215], v[78:81]
	v_mfma_f32_16x16x32_bf16 v[74:77], v[146:149], v[212:215], v[74:77]
	s_setprio 0
	s_setprio 1
	v_mfma_f32_16x16x32_bf16 v[118:121], v[150:153], v[184:187], v[118:121]
	v_mfma_f32_16x16x32_bf16 v[114:117], v[158:161], v[184:187], v[114:117]
	v_mfma_f32_16x16x32_bf16 v[102:105], v[150:153], v[192:195], v[102:105]
	v_mfma_f32_16x16x32_bf16 v[98:101], v[158:161], v[192:195], v[98:101]
	v_mfma_f32_16x16x32_bf16 v[86:89], v[150:153], v[200:203], v[86:89]
	v_mfma_f32_16x16x32_bf16 v[82:85], v[158:161], v[200:203], v[82:85]
	v_mfma_f32_16x16x32_bf16 v[70:73], v[150:153], v[208:211], v[70:73]
	v_mfma_f32_16x16x32_bf16 v[66:69], v[158:161], v[208:211], v[66:69]
	v_mfma_f32_16x16x32_bf16 v[118:121], v[154:157], v[188:191], v[118:121]
	v_mfma_f32_16x16x32_bf16 v[114:117], v[180:183], v[188:191], v[114:117]
	v_mfma_f32_16x16x32_bf16 v[102:105], v[154:157], v[196:199], v[102:105]
	v_mfma_f32_16x16x32_bf16 v[98:101], v[180:183], v[196:199], v[98:101]
	v_mfma_f32_16x16x32_bf16 v[86:89], v[154:157], v[204:207], v[86:89]
	v_mfma_f32_16x16x32_bf16 v[82:85], v[180:183], v[204:207], v[82:85]
	v_mfma_f32_16x16x32_bf16 v[70:73], v[154:157], v[212:215], v[70:73]
	v_mfma_f32_16x16x32_bf16 v[66:69], v[180:183], v[212:215], v[66:69]
	s_setprio 0
	s_barrier
	s_add_i32 s16, s16, s59
	s_mov_b32 m0, s16
	ds_read_b128 v[184:187], v179 offset:16384
	ds_read_b128 v[188:191], v179 offset:17408
	ds_read_b128 v[192:195], v179 offset:18432
	ds_read_b128 v[196:199], v179 offset:19456
	ds_read_b128 v[200:203], v179 offset:20480
	ds_read_b128 v[204:207], v179 offset:21504
	ds_read_b128 v[208:211], v179 offset:22528
	ds_read_b128 v[212:215], v179 offset:23552
	global_load_lds_dwordx4 v164, vcc
	s_add_i32 m0, s16, 0x2000
	s_add_i32 s16, s17, s59
	global_load_lds_dwordx4 v168, vcc
	s_add_u32 s98, vcc_lo, 0x80
	s_addc_u32 s99, vcc_hi, 0
	s_add_u32 vcc_lo, vcc_lo, s82
	s_addc_u32 vcc_hi, vcc_hi, 0
	s_mov_b32 m0, s16
	s_add_u32 s100, s52, 0x80
	s_addc_u32 s101, s53, 0
	global_load_lds_dwordx4 v164, vcc
	s_add_i32 m0, s16, 0x2000
	s_nop 0
	global_load_lds_dwordx4 v168, vcc
	s_mov_b32 m0, s60
	s_nop 0
	global_load_lds_dwordx4 v162, s[52:53]
	s_mov_b32 m0, s61
	s_nop 0
	global_load_lds_dwordx4 v166, s[52:53]
	s_waitcnt vmcnt(8)
	s_waitcnt lgkmcnt(0)
	s_barrier
; #define PG8_STAGE(bufoff, gbase, voff) do { _Pragma("unroll") for (int _i = 0; _i < 2; ++_i) \
;         __builtin_amdgcn_global_load_lds((const unsigned*)((const char*)(gbase) + (voff)[_i]), (PG8_LAS unsigned*)(lds + (bufoff) + ldsw + _i * 8192), 16, 0, 0); } while (0)
; #define PG8_LDA(dst, b, h) do { _Pragma("unroll") for (int m = 0; m < 4; ++m) _Pragma("unroll") for (int k = 0; k < 2; ++k) dst[m][k] = *(const PG8_LAS bf16x8*)(lds + PG8_SA(b, h) + aoff + m * 2048 + k * 1024); } while (0)
; #define PG8_LDB(dst, b, h) do { _Pragma("unroll") for (int n = 0; n < 2; ++n) _Pragma("unroll") for (int k = 0; k < 2; ++k) dst[n][k] = *(const PG8_LAS bf16x8*)(lds + PG8_SB(b, h) + boff + n * 2048 + k * 1024); } while (0)
; #define PG8_MMA(ai, bj, At, Bt) do { __builtin_amdgcn_s_setprio(1); _Pragma("unroll") for (int m = 0; m < 4; ++m) _Pragma("unroll") for (int n = 0; n < 2; ++n) _Pragma("unroll") for (int k = 0; k < 2; ++k) \
;         acc[ai][bj][m][n] = __builtin_amdgcn_mfma_f32_16x16x32_bf16(Bt[n][k], At[m][k], acc[ai][bj][m][n], 0, 0, 0); __builtin_amdgcn_s_setprio(0); } while (0)
; #define PG8_WAIT_V(n) asm volatile("s_waitcnt vmcnt(" #n ")" ::: "memory")
; #define PG8_WAIT_L(n) asm volatile("s_waitcnt lgkmcnt(" #n ")" ::: "memory")
; #define PG8_BAR __builtin_amdgcn_s_barrier()
; #define PG8_SCHED __builtin_amdgcn_sched_barrier(0)
; template <class Epi, class Sched, bool ALIGN_EPI = false, bool SP2 = false>
; __device__ __forceinline__ void gemm_phase(PG8_LAS unsigned char* lds, const Gemm g, const Sched& S, const Epi& E, const int tid_in) {
;     ...
;             PG8_WAIT_V(8); PG8_WAIT_L(0); PG8_BAR; PG8_MMA(1, 0, At, B0); PG8_MMA(1, 1, At, B1); PG8_BAR; PG8_SCHED;
;             PG8_LDB(B0, 1, 0); PG8_LDB(B1, 1, 1); PG8_SCHED; PG8_LDA(At, 1, 0); PG8_STAGE(PG8_SA(0, 1), a2 + hstep, voffA);
;             PG8_WAIT_V(8); PG8_WAIT_L(0); PG8_BAR; PG8_MMA(0, 0, At, B0); PG8_MMA(0, 1, At, B1); PG8_BAR; PG8_SCHED;
	s_setprio 1
	s_waitcnt lgkmcnt(0)
	v_mfma_f32_16x16x32_bf16 v[62:65], v[134:137], v[184:187], v[62:65]
	v_mfma_f32_16x16x32_bf16 v[58:61], v[142:145], v[184:187], v[58:61]
	v_mfma_f32_16x16x32_bf16 v[46:49], v[134:137], v[192:195], v[46:49]
	v_mfma_f32_16x16x32_bf16 v[42:45], v[142:145], v[192:195], v[42:45]
	v_mfma_f32_16x16x32_bf16 v[30:33], v[134:137], v[200:203], v[30:33]
	v_mfma_f32_16x16x32_bf16 v[26:29], v[142:145], v[200:203], v[26:29]
	v_mfma_f32_16x16x32_bf16 v[14:17], v[134:137], v[208:211], v[14:17]
	v_mfma_f32_16x16x32_bf16 v[10:13], v[142:145], v[208:211], v[10:13]
	v_mfma_f32_16x16x32_bf16 v[62:65], v[138:141], v[188:191], v[62:65]
	v_mfma_f32_16x16x32_bf16 v[58:61], v[146:149], v[188:191], v[58:61]
	v_mfma_f32_16x16x32_bf16 v[46:49], v[138:141], v[196:199], v[46:49]
	v_mfma_f32_16x16x32_bf16 v[42:45], v[146:149], v[196:199], v[42:45]
	v_mfma_f32_16x16x32_bf16 v[30:33], v[138:141], v[204:207], v[30:33]
	v_mfma_f32_16x16x32_bf16 v[26:29], v[146:149], v[204:207], v[26:29]
	v_mfma_f32_16x16x32_bf16 v[14:17], v[138:141], v[212:215], v[14:17]
	v_mfma_f32_16x16x32_bf16 v[10:13], v[146:149], v[212:215], v[10:13]
	s_setprio 0
	s_setprio 1
	v_mfma_f32_16x16x32_bf16 v[54:57], v[150:153], v[184:187], v[54:57]
	v_mfma_f32_16x16x32_bf16 v[50:53], v[158:161], v[184:187], v[50:53]
	v_mfma_f32_16x16x32_bf16 v[38:41], v[150:153], v[192:195], v[38:41]
	v_mfma_f32_16x16x32_bf16 v[34:37], v[158:161], v[192:195], v[34:37]
	v_mfma_f32_16x16x32_bf16 v[22:25], v[150:153], v[200:203], v[22:25]
	v_mfma_f32_16x16x32_bf16 v[18:21], v[158:161], v[200:203], v[18:21]
	v_mfma_f32_16x16x32_bf16 v[6:9], v[150:153], v[208:211], v[6:9]
	v_mfma_f32_16x16x32_bf16 v[2:5], v[158:161], v[208:211], v[2:5]
	v_mfma_f32_16x16x32_bf16 v[54:57], v[154:157], v[188:191], v[54:57]
	v_mfma_f32_16x16x32_bf16 v[50:53], v[180:183], v[188:191], v[50:53]
	v_mfma_f32_16x16x32_bf16 v[38:41], v[154:157], v[196:199], v[38:41]
	v_mfma_f32_16x16x32_bf16 v[34:37], v[180:183], v[196:199], v[34:37]
	v_mfma_f32_16x16x32_bf16 v[22:25], v[154:157], v[204:207], v[22:25]
	v_mfma_f32_16x16x32_bf16 v[18:21], v[180:183], v[204:207], v[18:21]
	v_mfma_f32_16x16x32_bf16 v[6:9], v[154:157], v[212:215], v[6:9]
	v_mfma_f32_16x16x32_bf16 v[2:5], v[180:183], v[212:215], v[2:5]
	s_setprio 0
	s_barrier
	ds_read_b128 v[134:137], v250
	ds_read_b128 v[138:141], v250 offset:1024
	ds_read_b128 v[142:145], v250 offset:2048
	ds_read_b128 v[146:149], v250 offset:3072
	ds_read_b128 v[150:153], v251
	ds_read_b128 v[154:157], v251 offset:1024
	ds_read_b128 v[158:161], v251 offset:2048
	ds_read_b128 v[180:183], v251 offset:3072
	s_add_i32 s16, 0, 0x18000
	s_add_i32 s17, 0, 0x1c000
	s_add_u32 s52, s52, s82
	s_addc_u32 s53, s53, 0
	s_mov_b32 m0, s62
	ds_read_b128 v[184:187], v179 offset:32768
	ds_read_b128 v[188:191], v179 offset:33792
	ds_read_b128 v[192:195], v179 offset:34816
	ds_read_b128 v[196:199], v179 offset:35840
	ds_read_b128 v[200:203], v179 offset:36864
	ds_read_b128 v[204:207], v179 offset:37888
	ds_read_b128 v[208:211], v179 offset:38912
	ds_read_b128 v[212:215], v179 offset:39936
	global_load_lds_dwordx4 v162, s[52:53]
	s_mov_b32 m0, s63
	s_nop 0
	global_load_lds_dwordx4 v166, s[52:53]
	s_waitcnt vmcnt(8)
	s_waitcnt lgkmcnt(0)
	s_barrier
	s_setprio 1
	s_waitcnt lgkmcnt(0)
	v_mfma_f32_16x16x32_bf16 v[126:129], v[134:137], v[184:187], v[126:129]
	v_mfma_f32_16x16x32_bf16 v[122:125], v[142:145], v[184:187], v[122:125]
	v_mfma_f32_16x16x32_bf16 v[110:113], v[134:137], v[192:195], v[110:113]
	v_mfma_f32_16x16x32_bf16 v[106:109], v[142:145], v[192:195], v[106:109]
	v_mfma_f32_16x16x32_bf16 v[94:97], v[134:137], v[200:203], v[94:97]
	v_mfma_f32_16x16x32_bf16 v[90:93], v[142:145], v[200:203], v[90:93]
	v_mfma_f32_16x16x32_bf16 v[78:81], v[134:137], v[208:211], v[78:81]
	v_mfma_f32_16x16x32_bf16 v[74:77], v[142:145], v[208:211], v[74:77]
	v_mfma_f32_16x16x32_bf16 v[126:129], v[138:141], v[188:191], v[126:129]
	v_mfma_f32_16x16x32_bf16 v[122:125], v[146:149], v[188:191], v[122:125]
	v_mfma_f32_16x16x32_bf16 v[110:113], v[138:141], v[196:199], v[110:113]
	v_mfma_f32_16x16x32_bf16 v[106:109], v[146:149], v[196:199], v[106:109]
	v_mfma_f32_16x16x32_bf16 v[94:97], v[138:141], v[204:207], v[94:97]
	v_mfma_f32_16x16x32_bf16 v[90:93], v[146:149], v[204:207], v[90:93]
	v_mfma_f32_16x16x32_bf16 v[78:81], v[138:141], v[212:215], v[78:81]
	v_mfma_f32_16x16x32_bf16 v[74:77], v[146:149], v[212:215], v[74:77]
	s_setprio 0
	s_setprio 1
	v_mfma_f32_16x16x32_bf16 v[118:121], v[150:153], v[184:187], v[118:121]
	v_mfma_f32_16x16x32_bf16 v[114:117], v[158:161], v[184:187], v[114:117]
	v_mfma_f32_16x16x32_bf16 v[102:105], v[150:153], v[192:195], v[102:105]
	v_mfma_f32_16x16x32_bf16 v[98:101], v[158:161], v[192:195], v[98:101]
	v_mfma_f32_16x16x32_bf16 v[86:89], v[150:153], v[200:203], v[86:89]
	v_mfma_f32_16x16x32_bf16 v[82:85], v[158:161], v[200:203], v[82:85]
	v_mfma_f32_16x16x32_bf16 v[70:73], v[150:153], v[208:211], v[70:73]
	v_mfma_f32_16x16x32_bf16 v[66:69], v[158:161], v[208:211], v[66:69]
	v_mfma_f32_16x16x32_bf16 v[118:121], v[154:157], v[188:191], v[118:121]
	v_mfma_f32_16x16x32_bf16 v[114:117], v[180:183], v[188:191], v[114:117]
	v_mfma_f32_16x16x32_bf16 v[102:105], v[154:157], v[196:199], v[102:105]
	v_mfma_f32_16x16x32_bf16 v[98:101], v[180:183], v[196:199], v[98:101]
	v_mfma_f32_16x16x32_bf16 v[86:89], v[154:157], v[204:207], v[86:89]
	v_mfma_f32_16x16x32_bf16 v[82:85], v[180:183], v[204:207], v[82:85]
	v_mfma_f32_16x16x32_bf16 v[70:73], v[154:157], v[212:215], v[70:73]
	v_mfma_f32_16x16x32_bf16 v[66:69], v[180:183], v[212:215], v[66:69]
	s_setprio 0
	s_barrier
; #define PG8_STAGE(bufoff, gbase, voff) do { _Pragma("unroll") for (int _i = 0; _i < 2; ++_i) \
;         __builtin_amdgcn_global_load_lds((const unsigned*)((const char*)(gbase) + (voff)[_i]), (PG8_LAS unsigned*)(lds + (bufoff) + ldsw + _i * 8192), 16, 0, 0); } while (0)
; #define PG8_LDA(dst, b, h) do { _Pragma("unroll") for (int m = 0; m < 4; ++m) _Pragma("unroll") for (int k = 0; k < 2; ++k) dst[m][k] = *(const PG8_LAS bf16x8*)(lds + PG8_SA(b, h) + aoff + m * 2048 + k * 1024); } while (0)
; #define PG8_MMA(ai, bj, At, Bt) do { __builtin_amdgcn_s_setprio(1); _Pragma("unroll") for (int m = 0; m < 4; ++m) _Pragma("unroll") for (int n = 0; n < 2; ++n) _Pragma("unroll") for (int k = 0; k < 2; ++k) \
;         acc[ai][bj][m][n] = __builtin_amdgcn_mfma_f32_16x16x32_bf16(Bt[n][k], At[m][k], acc[ai][bj][m][n], 0, 0, 0); __builtin_amdgcn_s_setprio(0); } while (0)
; #define PG8_WAIT_V(n) asm volatile("s_waitcnt vmcnt(" #n ")" ::: "memory")
; #define PG8_WAIT_L(n) asm volatile("s_waitcnt lgkmcnt(" #n ")" ::: "memory")
; #define PG8_BAR __builtin_amdgcn_s_barrier()
; #define PG8_SCHED __builtin_amdgcn_sched_barrier(0)
; template <class Epi, class Sched, bool ALIGN_EPI = false, bool SP2 = false>
; __device__ __forceinline__ void gemm_phase(PG8_LAS unsigned char* lds, const Gemm g, const Sched& S, const Epi& E, const int tid_in) {
;     ...
;         for (int t = 0; t < nt; t += 2) {
;             const bool last = (t == nt - 2);
;             const char* a1 = cA + (size_t)(t + 1) * kstep;
;             const char* a2 = last ? nA : cA + (size_t)(t + 2) * kstep; const char* b2 = last ? nB : cB + (size_t)(t + 2) * kstep;
;     ...
;             PG8_LDA(At, 1, 1); PG8_STAGE(PG8_SB(1, 0), b3, voffB); PG8_STAGE(PG8_SB(1, 1), b3 + hstep, voffB); PG8_STAGE(PG8_SA(1, 0), a3, voffA);
;             PG8_WAIT_V(8); PG8_WAIT_L(0); PG8_BAR; PG8_MMA(1, 0, At, B0); PG8_MMA(1, 1, At, B1); PG8_BAR; PG8_SCHED;
	s_add_i32 s16, s16, s59
	s_mov_b32 m0, s16
	ds_read_b128 v[184:187], v179 offset:49152
	ds_read_b128 v[188:191], v179 offset:50176
	ds_read_b128 v[192:195], v179 offset:51200
	ds_read_b128 v[196:199], v179 offset:52224
	ds_read_b128 v[200:203], v179 offset:53248
	ds_read_b128 v[204:207], v179 offset:54272
	ds_read_b128 v[208:211], v179 offset:55296
	ds_read_b128 v[212:215], v179 offset:56320
	global_load_lds_dwordx4 v164, s[98:99]
	s_add_i32 m0, s16, 0x2000
	s_add_i32 s16, s17, s59
	global_load_lds_dwordx4 v168, s[98:99]
	s_add_u32 vcc_lo, vcc_lo, 0x80
	s_addc_u32 vcc_hi, vcc_hi, 0
	s_mov_b32 m0, s16
	s_nop 0
	global_load_lds_dwordx4 v164, vcc
	s_add_i32 m0, s16, 0x2000
	s_nop 0
	global_load_lds_dwordx4 v168, vcc
	s_mov_b32 m0, s66
	s_nop 0
	global_load_lds_dwordx4 v162, s[100:101]
	s_mov_b32 m0, s67
	s_nop 0
	global_load_lds_dwordx4 v166, s[100:101]
	s_waitcnt vmcnt(8)
	s_waitcnt lgkmcnt(0)
	s_barrier
	s_setprio 1
	s_waitcnt lgkmcnt(0)
	v_mfma_f32_16x16x32_bf16 v[62:65], v[134:137], v[184:187], v[62:65]
	v_mfma_f32_16x16x32_bf16 v[58:61], v[142:145], v[184:187], v[58:61]
	v_mfma_f32_16x16x32_bf16 v[46:49], v[134:137], v[192:195], v[46:49]
	v_mfma_f32_16x16x32_bf16 v[42:45], v[142:145], v[192:195], v[42:45]
	v_mfma_f32_16x16x32_bf16 v[30:33], v[134:137], v[200:203], v[30:33]
	v_mfma_f32_16x16x32_bf16 v[26:29], v[142:145], v[200:203], v[26:29]
	v_mfma_f32_16x16x32_bf16 v[14:17], v[134:137], v[208:211], v[14:17]
	v_mfma_f32_16x16x32_bf16 v[10:13], v[142:145], v[208:211], v[10:13]
	v_mfma_f32_16x16x32_bf16 v[62:65], v[138:141], v[188:191], v[62:65]
	v_mfma_f32_16x16x32_bf16 v[58:61], v[146:149], v[188:191], v[58:61]
	v_mfma_f32_16x16x32_bf16 v[46:49], v[138:141], v[196:199], v[46:49]
	v_mfma_f32_16x16x32_bf16 v[42:45], v[146:149], v[196:199], v[42:45]
	v_mfma_f32_16x16x32_bf16 v[30:33], v[138:141], v[204:207], v[30:33]
	v_mfma_f32_16x16x32_bf16 v[26:29], v[146:149], v[204:207], v[26:29]
	v_mfma_f32_16x16x32_bf16 v[14:17], v[138:141], v[212:215], v[14:17]
	v_mfma_f32_16x16x32_bf16 v[10:13], v[146:149], v[212:215], v[10:13]
	s_setprio 0
	s_setprio 1
	v_mfma_f32_16x16x32_bf16 v[54:57], v[150:153], v[184:187], v[54:57]
	v_mfma_f32_16x16x32_bf16 v[50:53], v[158:161], v[184:187], v[50:53]
	v_mfma_f32_16x16x32_bf16 v[38:41], v[150:153], v[192:195], v[38:41]
	v_mfma_f32_16x16x32_bf16 v[34:37], v[158:161], v[192:195], v[34:37]
	v_mfma_f32_16x16x32_bf16 v[22:25], v[150:153], v[200:203], v[22:25]
	v_mfma_f32_16x16x32_bf16 v[18:21], v[158:161], v[200:203], v[18:21]
	v_mfma_f32_16x16x32_bf16 v[6:9], v[150:153], v[208:211], v[6:9]
	v_mfma_f32_16x16x32_bf16 v[2:5], v[158:161], v[208:211], v[2:5]
	v_mfma_f32_16x16x32_bf16 v[54:57], v[154:157], v[188:191], v[54:57]
	v_mfma_f32_16x16x32_bf16 v[50:53], v[180:183], v[188:191], v[50:53]
	v_mfma_f32_16x16x32_bf16 v[38:41], v[154:157], v[196:199], v[38:41]
	v_mfma_f32_16x16x32_bf16 v[34:37], v[180:183], v[196:199], v[34:37]
	v_mfma_f32_16x16x32_bf16 v[22:25], v[154:157], v[204:207], v[22:25]
	v_mfma_f32_16x16x32_bf16 v[18:21], v[180:183], v[204:207], v[18:21]
	v_mfma_f32_16x16x32_bf16 v[6:9], v[154:157], v[212:215], v[6:9]
	v_mfma_f32_16x16x32_bf16 v[2:5], v[180:183], v[212:215], v[2:5]
	s_setprio 0
	s_barrier
	s_add_u32 s10, s10, 0x100
	s_addc_u32 s11, s11, 0
	v_lshl_add_u64 v[132:133], v[132:133], 0, s[88:89]
	v_lshl_add_u64 v[130:131], v[130:131], 0, s[88:89]
	s_cmp_ge_u32 s77, s65
	s_mov_b32 s52, s77
	s_cbranch_scc0 .LBB0_115
	s_and_b64 vcc, exec, s[46:47]
	s_cbranch_vccz .LBB0_118
	s_barrier
